# M3 conv: packed FMA for the tap accumulation (v_pk_fma_f32 instead of v_pk_mul+v_pk_add), f32, one rounding fewer per tap
# baseline (speedup 1.0000x reference)
.LBB0_721:
	s_or_b64 exec, exec, s[0:1]
	v_lshlrev_b32_e32 v2, 3, v157
	s_lshl_b32 s4, s59, 2
	v_and_b32_e32 v156, 0x78, v2
	s_add_i32 s0, s4, 0
	v_lshl_add_u32 v198, v156, 2, s0
	v_ashrrev_i32_e32 v160, 3, v157
	v_and_b32_e32 v159, -2, v160
	v_lshlrev_b32_e32 v2, 1, v156
	v_mad_u32_u24 v124, v159, s48, v2
	v_add_u32_e32 v125, 0x110, v124
	s_mov_b32 s0, 0xbfb8aa3b
	s_mov_b32 vcc_lo, 0x3db504f3
	v_add_u32_e32 v3, 0x19000, v198
	ds_read_b128 v[162:165], v3
	ds_read_b128 v[166:169], v3 offset:4096
	ds_read_b128 v[170:173], v3 offset:8192
	ds_read_b128 v[174:177], v3 offset:12288
	v_lshlrev_b32_e32 v178, 16, v92
	v_and_b32_e32 v179, 0xffff0000, v92
	v_lshlrev_b32_e32 v180, 16, v93
	v_and_b32_e32 v181, 0xffff0000, v93
	v_lshlrev_b32_e32 v182, 16, v88
	v_and_b32_e32 v183, 0xffff0000, v88
	v_lshlrev_b32_e32 v184, 16, v89
	v_and_b32_e32 v185, 0xffff0000, v89
	v_lshlrev_b32_e32 v186, 16, v96
	v_and_b32_e32 v187, 0xffff0000, v96
	v_lshlrev_b32_e32 v188, 16, v97
	v_and_b32_e32 v189, 0xffff0000, v97
	v_lshlrev_b32_e32 v190, 16, v100
	v_and_b32_e32 v191, 0xffff0000, v100
	v_lshlrev_b32_e32 v192, 16, v101
	v_and_b32_e32 v193, 0xffff0000, v101
	v_lshlrev_b32_e32 v194, 16, v104
	v_and_b32_e32 v195, 0xffff0000, v104
	v_lshlrev_b32_e32 v196, 16, v105
	v_and_b32_e32 v197, 0xffff0000, v105
	s_waitcnt lgkmcnt(0)
	v_pk_mul_f32 v[108:109], v[162:163], v[178:179]
	v_pk_mul_f32 v[110:111], v[164:165], v[180:181]
	v_pk_mul_f32 v[112:113], v[162:163], v[182:183]
	v_pk_mul_f32 v[114:115], v[164:165], v[184:185]
	v_pk_fma_f32 v[108:109], v[166:167], v[182:183], v[108:109]
	v_pk_fma_f32 v[110:111], v[168:169], v[184:185], v[110:111]
	v_pk_fma_f32 v[112:113], v[166:167], v[186:187], v[112:113]
	v_pk_fma_f32 v[114:115], v[168:169], v[188:189], v[114:115]
	v_pk_fma_f32 v[108:109], v[170:171], v[186:187], v[108:109]
	v_pk_fma_f32 v[110:111], v[172:173], v[188:189], v[110:111]
	v_pk_fma_f32 v[112:113], v[170:171], v[190:191], v[112:113]
	v_pk_fma_f32 v[114:115], v[172:173], v[192:193], v[114:115]
	v_pk_fma_f32 v[108:109], v[174:175], v[190:191], v[108:109]
	v_pk_fma_f32 v[110:111], v[176:177], v[192:193], v[110:111]
	v_pk_fma_f32 v[112:113], v[174:175], v[194:195], v[112:113]
	v_pk_fma_f32 v[114:115], v[176:177], v[196:197], v[114:115]
	v_pk_mul_f32 v[116:117], v[108:109], s[0:1] op_sel_hi:[1,0]
	v_pk_mul_f32 v[118:119], v[110:111], s[0:1] op_sel_hi:[1,0]
	v_pk_mul_f32 v[120:121], v[112:113], s[0:1] op_sel_hi:[1,0]
	v_pk_mul_f32 v[122:123], v[114:115], s[0:1] op_sel_hi:[1,0]
	v_exp_f32_e32 v116, v116
	v_exp_f32_e32 v117, v117
	v_exp_f32_e32 v118, v118
	v_exp_f32_e32 v119, v119
	v_exp_f32_e32 v120, v120
	v_exp_f32_e32 v121, v121
	v_exp_f32_e32 v122, v122
	v_exp_f32_e32 v123, v123
	v_pk_add_f32 v[116:117], v[116:117], 1.0 op_sel_hi:[1,0]
	v_pk_add_f32 v[118:119], v[118:119], 1.0 op_sel_hi:[1,0]
	v_pk_add_f32 v[120:121], v[120:121], 1.0 op_sel_hi:[1,0]
	v_pk_add_f32 v[122:123], v[122:123], 1.0 op_sel_hi:[1,0]
	v_rcp_f32_e32 v116, v116
	v_rcp_f32_e32 v117, v117
	v_rcp_f32_e32 v118, v118
	v_rcp_f32_e32 v119, v119
	v_rcp_f32_e32 v120, v120
	v_rcp_f32_e32 v121, v121
	v_rcp_f32_e32 v122, v122
	v_rcp_f32_e32 v123, v123
	v_pk_mul_f32 v[92:93], v[108:109], v[116:117]
	v_pk_mul_f32 v[88:89], v[110:111], v[118:119]
	v_pk_mul_f32 v[96:97], v[112:113], v[120:121]
	v_pk_mul_f32 v[100:101], v[114:115], v[122:123]
	ds_read_b128 v[162:165], v3 offset:16
	ds_read_b128 v[166:169], v3 offset:4112
	ds_read_b128 v[170:173], v3 offset:8208
	ds_read_b128 v[174:177], v3 offset:12304
	v_lshlrev_b32_e32 v178, 16, v94
	v_and_b32_e32 v179, 0xffff0000, v94
	v_lshlrev_b32_e32 v180, 16, v95
	v_and_b32_e32 v181, 0xffff0000, v95
	v_lshlrev_b32_e32 v182, 16, v90
	v_and_b32_e32 v183, 0xffff0000, v90
	v_lshlrev_b32_e32 v184, 16, v91
	v_and_b32_e32 v185, 0xffff0000, v91
	v_lshlrev_b32_e32 v186, 16, v98
	v_and_b32_e32 v187, 0xffff0000, v98
	v_lshlrev_b32_e32 v188, 16, v99
	v_and_b32_e32 v189, 0xffff0000, v99
	v_lshlrev_b32_e32 v190, 16, v102
	v_and_b32_e32 v191, 0xffff0000, v102
	v_lshlrev_b32_e32 v192, 16, v103
	v_and_b32_e32 v193, 0xffff0000, v103
	v_lshlrev_b32_e32 v194, 16, v106
	v_and_b32_e32 v195, 0xffff0000, v106
	v_lshlrev_b32_e32 v196, 16, v107
	v_and_b32_e32 v197, 0xffff0000, v107
	s_waitcnt lgkmcnt(0)
	v_pk_mul_f32 v[108:109], v[162:163], v[178:179]
	v_pk_mul_f32 v[110:111], v[164:165], v[180:181]
	v_pk_mul_f32 v[112:113], v[162:163], v[182:183]
	v_pk_mul_f32 v[114:115], v[164:165], v[184:185]
	v_pk_fma_f32 v[108:109], v[166:167], v[182:183], v[108:109]
	v_pk_fma_f32 v[110:111], v[168:169], v[184:185], v[110:111]
	v_pk_fma_f32 v[112:113], v[166:167], v[186:187], v[112:113]
	v_pk_fma_f32 v[114:115], v[168:169], v[188:189], v[114:115]
	v_pk_fma_f32 v[108:109], v[170:171], v[186:187], v[108:109]
	v_pk_fma_f32 v[110:111], v[172:173], v[188:189], v[110:111]
	v_pk_fma_f32 v[112:113], v[170:171], v[190:191], v[112:113]
	v_pk_fma_f32 v[114:115], v[172:173], v[192:193], v[114:115]
	v_pk_fma_f32 v[108:109], v[174:175], v[190:191], v[108:109]
	v_pk_fma_f32 v[110:111], v[176:177], v[192:193], v[110:111]
	v_pk_fma_f32 v[112:113], v[174:175], v[194:195], v[112:113]
	v_pk_fma_f32 v[114:115], v[176:177], v[196:197], v[114:115]
	v_pk_mul_f32 v[116:117], v[108:109], s[0:1] op_sel_hi:[1,0]
	v_pk_mul_f32 v[118:119], v[110:111], s[0:1] op_sel_hi:[1,0]
	v_pk_mul_f32 v[120:121], v[112:113], s[0:1] op_sel_hi:[1,0]
	v_pk_mul_f32 v[122:123], v[114:115], s[0:1] op_sel_hi:[1,0]
	v_exp_f32_e32 v116, v116
	v_exp_f32_e32 v117, v117
	v_exp_f32_e32 v118, v118
	v_exp_f32_e32 v119, v119
	v_exp_f32_e32 v120, v120
	v_exp_f32_e32 v121, v121
	v_exp_f32_e32 v122, v122
	v_exp_f32_e32 v123, v123
	v_pk_add_f32 v[116:117], v[116:117], 1.0 op_sel_hi:[1,0]
	v_pk_add_f32 v[118:119], v[118:119], 1.0 op_sel_hi:[1,0]
	v_pk_add_f32 v[120:121], v[120:121], 1.0 op_sel_hi:[1,0]
	v_pk_add_f32 v[122:123], v[122:123], 1.0 op_sel_hi:[1,0]
	v_rcp_f32_e32 v116, v116
	v_rcp_f32_e32 v117, v117
	v_rcp_f32_e32 v118, v118
	v_rcp_f32_e32 v119, v119
	v_rcp_f32_e32 v120, v120
	v_rcp_f32_e32 v121, v121
	v_rcp_f32_e32 v122, v122
	v_rcp_f32_e32 v123, v123
	v_pk_mul_f32 v[108:109], v[108:109], v[116:117]
	v_pk_mul_f32 v[110:111], v[110:111], v[118:119]
	v_pk_mul_f32 v[112:113], v[112:113], v[120:121]
	v_pk_mul_f32 v[114:115], v[114:115], v[122:123]
	v_cvt_pk_bf16_f32 v116, v92, v93
	v_cvt_pk_bf16_f32 v117, v88, v89
	v_cvt_pk_bf16_f32 v118, v108, v109
	v_cvt_pk_bf16_f32 v119, v110, v111
	v_cvt_pk_bf16_f32 v120, v96, v97
	v_cvt_pk_bf16_f32 v121, v100, v101
	v_cvt_pk_bf16_f32 v122, v112, v113
	v_cvt_pk_bf16_f32 v123, v114, v115
	ds_write_b128 v124, v[116:119]
	ds_write_b128 v125, v[120:123]
	v_add_u32_e32 v3, 0x19800, v198
	ds_read_b128 v[162:165], v3
	ds_read_b128 v[166:169], v3 offset:4096
	ds_read_b128 v[170:173], v3 offset:8192
	ds_read_b128 v[174:177], v3 offset:12288
	v_lshlrev_b32_e32 v178, 16, v68
	v_and_b32_e32 v179, 0xffff0000, v68
	v_lshlrev_b32_e32 v180, 16, v69
	v_and_b32_e32 v181, 0xffff0000, v69
	v_lshlrev_b32_e32 v182, 16, v76
	v_and_b32_e32 v183, 0xffff0000, v76
	v_lshlrev_b32_e32 v184, 16, v77
	v_and_b32_e32 v185, 0xffff0000, v77
	v_lshlrev_b32_e32 v186, 16, v72
	v_and_b32_e32 v187, 0xffff0000, v72
	v_lshlrev_b32_e32 v188, 16, v73
	v_and_b32_e32 v189, 0xffff0000, v73
	v_lshlrev_b32_e32 v190, 16, v80
	v_and_b32_e32 v191, 0xffff0000, v80
	v_lshlrev_b32_e32 v192, 16, v81
	v_and_b32_e32 v193, 0xffff0000, v81
	v_lshlrev_b32_e32 v194, 16, v84
	v_and_b32_e32 v195, 0xffff0000, v84
	v_lshlrev_b32_e32 v196, 16, v85
	v_and_b32_e32 v197, 0xffff0000, v85
	s_waitcnt lgkmcnt(0)
	v_pk_mul_f32 v[108:109], v[162:163], v[178:179]
	v_pk_mul_f32 v[110:111], v[164:165], v[180:181]
	v_pk_mul_f32 v[112:113], v[162:163], v[182:183]
	v_pk_mul_f32 v[114:115], v[164:165], v[184:185]
	v_pk_fma_f32 v[108:109], v[166:167], v[182:183], v[108:109]
	v_pk_fma_f32 v[110:111], v[168:169], v[184:185], v[110:111]
	v_pk_fma_f32 v[112:113], v[166:167], v[186:187], v[112:113]
	v_pk_fma_f32 v[114:115], v[168:169], v[188:189], v[114:115]
	v_pk_fma_f32 v[108:109], v[170:171], v[186:187], v[108:109]
	v_pk_fma_f32 v[110:111], v[172:173], v[188:189], v[110:111]
	v_pk_fma_f32 v[112:113], v[170:171], v[190:191], v[112:113]
	v_pk_fma_f32 v[114:115], v[172:173], v[192:193], v[114:115]
	v_pk_fma_f32 v[108:109], v[174:175], v[190:191], v[108:109]
	v_pk_fma_f32 v[110:111], v[176:177], v[192:193], v[110:111]
	v_pk_fma_f32 v[112:113], v[174:175], v[194:195], v[112:113]
	v_pk_fma_f32 v[114:115], v[176:177], v[196:197], v[114:115]
	v_pk_mul_f32 v[116:117], v[108:109], s[0:1] op_sel_hi:[1,0]
	v_pk_mul_f32 v[118:119], v[110:111], s[0:1] op_sel_hi:[1,0]
	v_pk_mul_f32 v[120:121], v[112:113], s[0:1] op_sel_hi:[1,0]
	v_pk_mul_f32 v[122:123], v[114:115], s[0:1] op_sel_hi:[1,0]
	v_exp_f32_e32 v116, v116
	v_exp_f32_e32 v117, v117
	v_exp_f32_e32 v118, v118
	v_exp_f32_e32 v119, v119
	v_exp_f32_e32 v120, v120
	v_exp_f32_e32 v121, v121
	v_exp_f32_e32 v122, v122
	v_exp_f32_e32 v123, v123
	v_pk_add_f32 v[116:117], v[116:117], 1.0 op_sel_hi:[1,0]
	v_pk_add_f32 v[118:119], v[118:119], 1.0 op_sel_hi:[1,0]
	v_pk_add_f32 v[120:121], v[120:121], 1.0 op_sel_hi:[1,0]
	v_pk_add_f32 v[122:123], v[122:123], 1.0 op_sel_hi:[1,0]
	v_rcp_f32_e32 v116, v116
	v_rcp_f32_e32 v117, v117
	v_rcp_f32_e32 v118, v118
	v_rcp_f32_e32 v119, v119
	v_rcp_f32_e32 v120, v120
	v_rcp_f32_e32 v121, v121
	v_rcp_f32_e32 v122, v122
	v_rcp_f32_e32 v123, v123
	v_pk_mul_f32 v[68:69], v[108:109], v[116:117]
	v_pk_mul_f32 v[76:77], v[110:111], v[118:119]
	v_pk_mul_f32 v[72:73], v[112:113], v[120:121]
	v_pk_mul_f32 v[80:81], v[114:115], v[122:123]
	ds_read_b128 v[162:165], v3 offset:16
	ds_read_b128 v[166:169], v3 offset:4112
	ds_read_b128 v[170:173], v3 offset:8208
	ds_read_b128 v[174:177], v3 offset:12304
	v_lshlrev_b32_e32 v178, 16, v70
	v_and_b32_e32 v179, 0xffff0000, v70
	v_lshlrev_b32_e32 v180, 16, v71
	v_and_b32_e32 v181, 0xffff0000, v71
	v_lshlrev_b32_e32 v182, 16, v78
	v_and_b32_e32 v183, 0xffff0000, v78
	v_lshlrev_b32_e32 v184, 16, v79
	v_and_b32_e32 v185, 0xffff0000, v79
	v_lshlrev_b32_e32 v186, 16, v74
	v_and_b32_e32 v187, 0xffff0000, v74
	v_lshlrev_b32_e32 v188, 16, v75
	v_and_b32_e32 v189, 0xffff0000, v75
	v_lshlrev_b32_e32 v190, 16, v82
	v_and_b32_e32 v191, 0xffff0000, v82
	v_lshlrev_b32_e32 v192, 16, v83
	v_and_b32_e32 v193, 0xffff0000, v83
	v_lshlrev_b32_e32 v194, 16, v86
	v_and_b32_e32 v195, 0xffff0000, v86
	v_lshlrev_b32_e32 v196, 16, v87
	v_and_b32_e32 v197, 0xffff0000, v87
	s_waitcnt lgkmcnt(0)
	v_pk_mul_f32 v[108:109], v[162:163], v[178:179]
	v_pk_mul_f32 v[110:111], v[164:165], v[180:181]
	v_pk_mul_f32 v[112:113], v[162:163], v[182:183]
	v_pk_mul_f32 v[114:115], v[164:165], v[184:185]
	v_pk_fma_f32 v[108:109], v[166:167], v[182:183], v[108:109]
	v_pk_fma_f32 v[110:111], v[168:169], v[184:185], v[110:111]
	v_pk_fma_f32 v[112:113], v[166:167], v[186:187], v[112:113]
	v_pk_fma_f32 v[114:115], v[168:169], v[188:189], v[114:115]
	v_pk_fma_f32 v[108:109], v[170:171], v[186:187], v[108:109]
	v_pk_fma_f32 v[110:111], v[172:173], v[188:189], v[110:111]
	v_pk_fma_f32 v[112:113], v[170:171], v[190:191], v[112:113]
	v_pk_fma_f32 v[114:115], v[172:173], v[192:193], v[114:115]
	v_pk_fma_f32 v[108:109], v[174:175], v[190:191], v[108:109]
	v_pk_fma_f32 v[110:111], v[176:177], v[192:193], v[110:111]
	v_pk_fma_f32 v[112:113], v[174:175], v[194:195], v[112:113]
	v_pk_fma_f32 v[114:115], v[176:177], v[196:197], v[114:115]
	v_pk_mul_f32 v[116:117], v[108:109], s[0:1] op_sel_hi:[1,0]
	v_pk_mul_f32 v[118:119], v[110:111], s[0:1] op_sel_hi:[1,0]
	v_pk_mul_f32 v[120:121], v[112:113], s[0:1] op_sel_hi:[1,0]
	v_pk_mul_f32 v[122:123], v[114:115], s[0:1] op_sel_hi:[1,0]
	v_exp_f32_e32 v116, v116
	v_exp_f32_e32 v117, v117
	v_exp_f32_e32 v118, v118
	v_exp_f32_e32 v119, v119
	v_exp_f32_e32 v120, v120
	v_exp_f32_e32 v121, v121
	v_exp_f32_e32 v122, v122
	v_exp_f32_e32 v123, v123
	v_pk_add_f32 v[116:117], v[116:117], 1.0 op_sel_hi:[1,0]
	v_pk_add_f32 v[118:119], v[118:119], 1.0 op_sel_hi:[1,0]
	v_pk_add_f32 v[120:121], v[120:121], 1.0 op_sel_hi:[1,0]
	v_pk_add_f32 v[122:123], v[122:123], 1.0 op_sel_hi:[1,0]
	v_rcp_f32_e32 v116, v116
	v_rcp_f32_e32 v117, v117
	v_rcp_f32_e32 v118, v118
	v_rcp_f32_e32 v119, v119
	v_rcp_f32_e32 v120, v120
	v_rcp_f32_e32 v121, v121
	v_rcp_f32_e32 v122, v122
	v_rcp_f32_e32 v123, v123
	v_pk_mul_f32 v[108:109], v[108:109], v[116:117]
	v_pk_mul_f32 v[110:111], v[110:111], v[118:119]
	v_pk_mul_f32 v[112:113], v[112:113], v[120:121]
	v_pk_mul_f32 v[114:115], v[114:115], v[122:123]
	v_pk_mul_f32 v[68:69], v[68:69], vcc op_sel_hi:[1,0]
	v_pk_mul_f32 v[76:77], v[76:77], vcc op_sel_hi:[1,0]
	v_pk_mul_f32 v[72:73], v[72:73], vcc op_sel_hi:[1,0]
	v_pk_mul_f32 v[80:81], v[80:81], vcc op_sel_hi:[1,0]
	v_pk_mul_f32 v[108:109], v[108:109], vcc op_sel_hi:[1,0]
	v_pk_mul_f32 v[110:111], v[110:111], vcc op_sel_hi:[1,0]
	v_pk_mul_f32 v[112:113], v[112:113], vcc op_sel_hi:[1,0]
	v_pk_mul_f32 v[114:115], v[114:115], vcc op_sel_hi:[1,0]
	v_cvt_pk_bf16_f32 v116, v68, v69
	v_cvt_pk_bf16_f32 v117, v76, v77
	v_cvt_pk_bf16_f32 v118, v108, v109
	v_cvt_pk_bf16_f32 v119, v110, v111
	v_cvt_pk_bf16_f32 v120, v72, v73
	v_cvt_pk_bf16_f32 v121, v80, v81
	v_cvt_pk_bf16_f32 v122, v112, v113
	v_cvt_pk_bf16_f32 v123, v114, v115
	ds_write_b128 v124, v[116:119] offset:17408
	ds_write_b128 v125, v[120:123] offset:17408
	v_cmp_gt_i32_e32 vcc, s49, v157
	s_and_saveexec_b64 s[0:1], vcc
	v_lshl_add_u32 v2, v157, 2, 0
	v_add_u32_e32 v2, 0x18500, v2
	ds_write_b32 v2, v158
	s_or_b64 exec, exec, s[0:1]
	v_ashrrev_i32_e32 v91, 6, v157
	v_ashrrev_i32_e32 v76, 7, v157
	v_and_b32_e32 v88, 15, v157
	v_lshlrev_b32_e32 v2, 1, v91
	v_lshlrev_b32_e32 v73, 4, v76
	v_and_b32_e32 v3, 48, v161
	v_and_b32_e32 v77, 2, v2
	v_or_b32_e32 v2, v73, v88
	v_add_u32_e32 v72, 0, v3
	v_mad_u64_u32 v[2:3], s[0:1], v2, s48, v[72:73]
	v_cmp_gt_i32_e64 s[14:15], v77, v76
	v_cmp_le_i32_e32 vcc, v77, v76
	v_lshl_or_b32 v80, v77, 4, v88
	v_mov_b32_e32 v68, 0
	v_mov_b32_e32 v69, 0
	v_mov_b32_e32 v70, 0
	v_mov_b32_e32 v71, 0
	s_waitcnt lgkmcnt(0)
	s_barrier
	s_and_saveexec_b64 s[0:1], vcc
	s_cbranch_execz .LBB0_725
	ds_read_b128 v[68:71], v2
	v_mad_u32_u24 v3, v80, s48, v72
	ds_read_b128 v[82:85], v2 offset:64
	ds_read_b128 v[92:95], v3 offset:17408
	ds_read_b128 v[96:99], v3 offset:17472
	s_waitcnt lgkmcnt(1)
	v_mfma_f32_16x16x32_bf16 v[68:71], v[68:71], v[92:95], 0
	ds_read_b128 v[92:95], v2 offset:128
	ds_read_b128 v[100:103], v2 offset:192
	s_waitcnt lgkmcnt(2)
	v_mfma_f32_16x16x32_bf16 v[68:71], v[82:85], v[96:99], v[68:71]
	ds_read_b128 v[82:85], v3 offset:17536
	ds_read_b128 v[96:99], v3 offset:17600
	s_waitcnt lgkmcnt(1)
	v_mfma_f32_16x16x32_bf16 v[68:71], v[92:95], v[82:85], v[68:71]
	s_waitcnt lgkmcnt(0)
	v_mfma_f32_16x16x32_bf16 v[68:71], v[100:103], v[96:99], v[68:71]
